# stack12 + nt streaming policy on the read-once f32 weight loads of the deferred conversion (P2 tail and attention phase)
# speedup vs baseline: 1.0012x; 1.0012x over previous
.LBB8_288:
	v_ashrrev_i32_e32 v131, 3, v64
	v_and_b32_e32 v134, -2, v131
	v_readlane_b32 s29, v254, 4
	s_waitcnt vmcnt(0)
	v_lshl_add_u32 v58, v132, 6, v134
	s_mul_i32 s1, s29, 0x4100
	v_mad_i64_i32 v[0:1], s[6:7], s0, v58, 0
	v_or_b32_e32 v2, 1, v58
	v_add_u32_e32 v8, 8, v58
	v_add_u32_e32 v10, 9, v58
	v_add_u32_e32 v16, 16, v58
	v_add_u32_e32 v18, 17, v58
	v_add_u32_e32 v24, 24, v58
	v_add_u32_e32 v26, 25, v58
	v_add_u32_e32 v32, 32, v58
	v_add_u32_e32 v34, 33, v58
	v_add_u32_e32 v40, 40, v58
	v_add_u32_e32 v42, 41, v58
	v_add_u32_e32 v48, 48, v58
	v_add_u32_e32 v50, 49, v58
	v_add_u32_e32 v56, 56, v58
	v_add_u32_e32 v58, 57, v58
	s_add_i32 s8, s1, 0
	v_lshlrev_b32_e32 v65, 2, v64
	s_ashr_i32 s61, s60, 31
	v_mad_i64_i32 v[2:3], s[10:11], s0, v2, 0
	v_mad_i64_i32 v[8:9], s[10:11], s0, v8, 0
	v_mad_i64_i32 v[10:11], s[10:11], s0, v10, 0
	v_mad_i64_i32 v[16:17], s[10:11], s0, v16, 0
	v_mad_i64_i32 v[18:19], s[10:11], s0, v18, 0
	v_mad_i64_i32 v[24:25], s[10:11], s0, v24, 0
	v_mad_i64_i32 v[26:27], s[10:11], s0, v26, 0
	v_mad_i64_i32 v[32:33], s[10:11], s0, v32, 0
	v_mad_i64_i32 v[34:35], s[10:11], s0, v34, 0
	v_mad_i64_i32 v[40:41], s[10:11], s0, v40, 0
	v_mad_i64_i32 v[42:43], s[10:11], s0, v42, 0
	v_mad_i64_i32 v[48:49], s[10:11], s0, v48, 0
	v_mad_i64_i32 v[50:51], s[10:11], s0, v50, 0
	v_mad_i64_i32 v[56:57], s[10:11], s0, v56, 0
	v_mad_i64_i32 v[58:59], s[0:1], s0, v58, 0
	v_and_b32_e32 v66, 60, v65
	v_lshl_add_u64 v[0:1], v[0:1], 2, s[4:5]
	s_lshl_b64 s[6:7], s[60:61], 2
	v_lshl_add_u64 v[2:3], v[2:3], 2, s[4:5]
	v_lshl_add_u64 v[8:9], v[8:9], 2, s[4:5]
	v_lshl_add_u64 v[10:11], v[10:11], 2, s[4:5]
	v_lshl_add_u64 v[16:17], v[16:17], 2, s[4:5]
	v_lshl_add_u64 v[18:19], v[18:19], 2, s[4:5]
	v_lshl_add_u64 v[24:25], v[24:25], 2, s[4:5]
	v_lshl_add_u64 v[26:27], v[26:27], 2, s[4:5]
	v_lshl_add_u64 v[32:33], v[32:33], 2, s[4:5]
	v_lshl_add_u64 v[34:35], v[34:35], 2, s[4:5]
	v_lshl_add_u64 v[40:41], v[40:41], 2, s[4:5]
	v_lshl_add_u64 v[42:43], v[42:43], 2, s[4:5]
	v_lshl_add_u64 v[48:49], v[48:49], 2, s[4:5]
	v_lshl_add_u64 v[50:51], v[50:51], 2, s[4:5]
	v_lshl_add_u64 v[56:57], v[56:57], 2, s[4:5]
	v_lshl_add_u64 v[58:59], v[58:59], 2, s[4:5]
	v_mov_b32_e32 v129, 0
	v_lshl_add_u64 v[0:1], v[0:1], 0, s[6:7]
	v_lshlrev_b32_e32 v128, 2, v66
	v_lshl_add_u64 v[2:3], v[2:3], 0, s[6:7]
	v_lshl_add_u64 v[8:9], v[8:9], 0, s[6:7]
	v_lshl_add_u64 v[10:11], v[10:11], 0, s[6:7]
	v_lshl_add_u64 v[16:17], v[16:17], 0, s[6:7]
	v_lshl_add_u64 v[18:19], v[18:19], 0, s[6:7]
	v_lshl_add_u64 v[24:25], v[24:25], 0, s[6:7]
	v_lshl_add_u64 v[26:27], v[26:27], 0, s[6:7]
	v_lshl_add_u64 v[32:33], v[32:33], 0, s[6:7]
	v_lshl_add_u64 v[34:35], v[34:35], 0, s[6:7]
	v_lshl_add_u64 v[40:41], v[40:41], 0, s[6:7]
	v_lshl_add_u64 v[42:43], v[42:43], 0, s[6:7]
	v_lshl_add_u64 v[48:49], v[48:49], 0, s[6:7]
	v_lshl_add_u64 v[50:51], v[50:51], 0, s[6:7]
	v_lshl_add_u64 v[56:57], v[56:57], 0, s[6:7]
	v_lshl_add_u64 v[58:59], v[58:59], 0, s[6:7]
	v_lshl_add_u64 v[0:1], v[0:1], 0, v[128:129]
	v_lshl_add_u64 v[4:5], v[2:3], 0, v[128:129]
	v_lshl_add_u64 v[8:9], v[8:9], 0, v[128:129]
	v_lshl_add_u64 v[12:13], v[10:11], 0, v[128:129]
	v_lshl_add_u64 v[16:17], v[16:17], 0, v[128:129]
	v_lshl_add_u64 v[20:21], v[18:19], 0, v[128:129]
	v_lshl_add_u64 v[24:25], v[24:25], 0, v[128:129]
	v_lshl_add_u64 v[28:29], v[26:27], 0, v[128:129]
	v_lshl_add_u64 v[32:33], v[32:33], 0, v[128:129]
	v_lshl_add_u64 v[36:37], v[34:35], 0, v[128:129]
	v_lshl_add_u64 v[40:41], v[40:41], 0, v[128:129]
	v_lshl_add_u64 v[44:45], v[42:43], 0, v[128:129]
	v_lshl_add_u64 v[48:49], v[48:49], 0, v[128:129]
	v_lshl_add_u64 v[52:53], v[50:51], 0, v[128:129]
	v_lshl_add_u64 v[56:57], v[56:57], 0, v[128:129]
	v_lshl_add_u64 v[60:61], v[58:59], 0, v[128:129]
	global_load_dwordx4 v[0:3], v[0:1], off nt
	s_nop 0
	global_load_dwordx4 v[4:7], v[4:5], off nt
	s_nop 0
	global_load_dwordx4 v[8:11], v[8:9], off nt
	s_nop 0
	global_load_dwordx4 v[12:15], v[12:13], off nt
	s_nop 0
	global_load_dwordx4 v[16:19], v[16:17], off nt
	s_nop 0
	global_load_dwordx4 v[20:23], v[20:21], off nt
	s_nop 0
	global_load_dwordx4 v[24:27], v[24:25], off nt
	s_nop 0
	global_load_dwordx4 v[28:31], v[28:29], off nt
	s_nop 0
	global_load_dwordx4 v[32:35], v[32:33], off nt
	s_nop 0
	global_load_dwordx4 v[36:39], v[36:37], off nt
	s_nop 0
	global_load_dwordx4 v[40:43], v[40:41], off nt
	s_nop 0
	global_load_dwordx4 v[44:47], v[44:45], off nt
	s_nop 0
	global_load_dwordx4 v[48:51], v[48:49], off nt
	s_nop 0
	global_load_dwordx4 v[52:55], v[52:53], off nt
	s_nop 0
	global_load_dwordx4 v[56:59], v[56:57], off nt
	s_nop 0
	global_load_dwordx4 v[60:63], v[60:61], off nt
	v_add_u32_e32 v135, 8, v131
	v_bitop3_b32 v77, v135, 28, v65 bitop3:0x48
	v_lshlrev_b32_e32 v76, 7, v135
	v_lshlrev_b32_e32 v77, 2, v77
	v_add_u32_e32 v137, 16, v131
	v_add3_u32 v136, s8, v76, v77
	v_bitop3_b32 v77, v137, 28, v65 bitop3:0x48
	v_lshlrev_b32_e32 v76, 7, v137
	v_lshlrev_b32_e32 v77, 2, v77
	v_add_u32_e32 v139, 24, v131
	v_add3_u32 v138, s8, v76, v77
	v_bitop3_b32 v77, v139, 28, v65 bitop3:0x48
	v_lshlrev_b32_e32 v76, 7, v139
	v_lshlrev_b32_e32 v77, 2, v77
	s_lshl_b32 s28, s2, 3
	v_add3_u32 v140, s8, v76, v77
	v_add_u32_e32 v141, 32, v131
	v_bitop3_b32 v77, v131, 28, v65 bitop3:0x48
	v_add_u32_e32 v143, 40, v131
	s_add_i32 s28, s29, s28
	s_lshl_b32 s29, s38, 3
	v_lshlrev_b32_e32 v76, 7, v141
	v_lshlrev_b32_e32 v77, 2, v77
	v_bitop3_b32 v78, v143, 28, v65 bitop3:0x48
	s_add_i32 s29, s28, s29
	s_lshl_b32 s52, s3, 3
	v_ashrrev_i32_e32 v67, 4, v64
	v_add3_u32 v142, s8, v76, v77
	v_lshlrev_b32_e32 v76, 7, v143
	v_lshlrev_b32_e32 v78, 2, v78
	v_add_u32_e32 v145, 48, v131
	s_sub_i32 s29, s29, s52
	s_lshl_b32 s53, s56, 3
	v_bitop3_b32 v68, v65, v67, 28 bitop3:0x6c
	v_add_u32_e32 v70, 4, v67
	v_add_u32_e32 v71, 8, v67
	v_add_u32_e32 v72, 12, v67
	v_add_u32_e32 v73, 16, v67
	v_add_u32_e32 v74, 20, v67
	v_add_u32_e32 v75, 24, v67
	v_add_u32_e32 v67, 28, v67
	v_add3_u32 v144, s8, v76, v78
	v_bitop3_b32 v78, v145, 28, v65 bitop3:0x48
	v_add_u32_e32 v147, 56, v131
	s_sub_i32 s58, s29, s53
	s_lshl_b32 s29, s38, 4
	s_mul_i32 s38, s38, 24
	v_bitop3_b32 v70, v70, v65, 28 bitop3:0x78
	v_bitop3_b32 v71, v71, v65, 28 bitop3:0x78
	v_bitop3_b32 v72, v72, v65, 28 bitop3:0x78
	v_bitop3_b32 v73, v73, v65, 28 bitop3:0x78
	v_bitop3_b32 v74, v74, v65, 28 bitop3:0x78
	v_bitop3_b32 v75, v75, v65, 28 bitop3:0x78
	v_bitop3_b32 v67, v67, v65, 28 bitop3:0x78
	v_lshlrev_b32_e32 v76, 7, v145
	v_lshlrev_b32_e32 v78, 2, v78
	v_bitop3_b32 v65, v147, 28, v65 bitop3:0x48
	v_lshlrev_b32_e32 v64, 3, v64
	s_add_i32 s38, s28, s38
	s_add_i32 s28, s28, s29
	v_lshl_add_u32 v68, v68, 2, s8
	v_lshlrev_b32_e32 v69, 7, v66
	v_lshl_add_u32 v70, v70, 2, s8
	v_lshl_add_u32 v71, v71, 2, s8
	v_lshl_add_u32 v72, v72, 2, s8
	v_lshl_add_u32 v73, v73, 2, s8
	v_lshl_add_u32 v74, v74, 2, s8
	v_lshl_add_u32 v75, v75, 2, s8
	v_lshl_add_u32 v67, v67, 2, s8
	v_add3_u32 v146, s8, v76, v78
	v_lshlrev_b32_e32 v76, 7, v147
	v_lshlrev_b32_e32 v65, 2, v65
	v_and_b32_e32 v130, 56, v64
	v_lshlrev_b32_e32 v64, 7, v131
	s_lshl_b32 s53, s56, 4
	s_sub_i32 s38, s38, s52
	s_mul_i32 s56, s56, 24
	s_sub_i32 s28, s28, s52
	s_mov_b32 s57, 0
	v_add3_u32 v148, s8, v76, v65
	v_cmp_gt_i32_e64 s[0:1], 64, v131
	v_add3_u32 v149, s8, v64, v77
	v_cmp_gt_i32_e64 s[16:17], 56, v131
	v_cmp_gt_i32_e64 s[4:5], 48, v131
	v_cmp_gt_i32_e64 s[6:7], 40, v131
	v_cmp_gt_i32_e64 s[8:9], 32, v131
	v_cmp_gt_i32_e64 s[10:11], 24, v131
	v_cmp_gt_i32_e64 s[12:13], 16, v131
	v_cmp_gt_i32_e64 s[14:15], 8, v131
	s_sub_i32 s59, s29, s53
	s_sub_i32 s38, s38, s56
	s_sub_i32 s56, s28, s53
	v_lshlrev_b32_e32 v128, 2, v66
	v_add_u32_e32 v150, v68, v69
	v_add_u32_e32 v151, v70, v69
	v_add_u32_e32 v152, v71, v69
	v_add_u32_e32 v153, v72, v69
	v_add_u32_e32 v154, v73, v69
	v_add_u32_e32 v155, v74, v69
	v_add_u32_e32 v156, v75, v69
	v_add_u32_e32 v157, v67, v69
	s_branch .LBB8_291

.LBB8_305:
	s_lshl_b32 s74, s78, 6
	s_waitcnt vmcnt(1)
	v_add_u32_e32 v122, s74, v134
	s_waitcnt lgkmcnt(2)
	v_add_u32_e32 v72, 8, v122
	v_add_u32_e32 v80, 16, v122
	v_add_u32_e32 v88, 24, v122
	v_add_u32_e32 v96, 32, v122
	v_add_u32_e32 v104, 40, v122
	v_add_u32_e32 v112, 48, v122
	s_waitcnt lgkmcnt(0)
	v_ashrrev_i32_e32 v64, 31, v122
	v_ashrrev_i32_e32 v73, 31, v72
	v_ashrrev_i32_e32 v81, 31, v80
	v_ashrrev_i32_e32 v89, 31, v88
	v_ashrrev_i32_e32 v97, 31, v96
	v_ashrrev_i32_e32 v105, 31, v104
	v_ashrrev_i32_e32 v113, 31, v112
	v_add_u32_e32 v120, 56, v122
	v_mul_lo_u32 v68, s80, v64
	v_mul_lo_u32 v66, s81, v122
	v_mad_u64_u32 v[64:65], s[78:79], s80, v122, 0
	v_mul_lo_u32 v74, s80, v73
	v_mul_lo_u32 v75, s81, v72
	v_mad_u64_u32 v[72:73], s[78:79], s80, v72, 0
	v_mul_lo_u32 v82, s80, v81
	v_mul_lo_u32 v83, s81, v80
	v_mad_u64_u32 v[80:81], s[78:79], s80, v80, 0
	v_mul_lo_u32 v90, s80, v89
	v_mul_lo_u32 v91, s81, v88
	v_mad_u64_u32 v[88:89], s[78:79], s80, v88, 0
	v_mul_lo_u32 v98, s80, v97
	v_mul_lo_u32 v99, s81, v96
	v_mad_u64_u32 v[96:97], s[78:79], s80, v96, 0
	v_mul_lo_u32 v106, s80, v105
	v_mul_lo_u32 v107, s81, v104
	v_mad_u64_u32 v[104:105], s[78:79], s80, v104, 0
	v_mul_lo_u32 v114, s80, v113
	v_mul_lo_u32 v115, s81, v112
	v_mad_u64_u32 v[112:113], s[78:79], s80, v112, 0
	v_ashrrev_i32_e32 v121, 31, v120
	v_add3_u32 v65, v65, v68, v66
	v_or_b32_e32 v66, 1, v122
	v_add3_u32 v73, v73, v74, v75
	v_add_u32_e32 v74, 9, v122
	v_add3_u32 v81, v81, v82, v83
	v_add_u32_e32 v82, 17, v122
	v_add3_u32 v89, v89, v90, v91
	v_add_u32_e32 v90, 25, v122
	v_add3_u32 v97, v97, v98, v99
	v_add_u32_e32 v98, 33, v122
	v_add3_u32 v105, v105, v106, v107
	v_add_u32_e32 v106, 41, v122
	v_add3_u32 v113, v113, v114, v115
	v_add_u32_e32 v114, 49, v122
	v_mul_lo_u32 v123, s80, v121
	s_waitcnt vmcnt(0)
	v_mul_lo_u32 v124, s81, v120
	v_mad_u64_u32 v[120:121], s[78:79], s80, v120, 0
	v_add_u32_e32 v122, 57, v122
	v_ashrrev_i32_e32 v75, 31, v74
	v_ashrrev_i32_e32 v83, 31, v82
	v_ashrrev_i32_e32 v91, 31, v90
	v_ashrrev_i32_e32 v99, 31, v98
	v_ashrrev_i32_e32 v107, 31, v106
	v_ashrrev_i32_e32 v115, 31, v114
	v_add3_u32 v121, v121, v123, v124
	v_ashrrev_i32_e32 v123, 31, v122
	v_mul_lo_u32 v69, s81, v66
	v_mad_u64_u32 v[66:67], s[78:79], s80, v66, 0
	v_mul_lo_u32 v76, s80, v75
	v_mul_lo_u32 v77, s81, v74
	v_mad_u64_u32 v[74:75], s[78:79], s80, v74, 0
	v_mul_lo_u32 v84, s80, v83
	v_mul_lo_u32 v85, s81, v82
	v_mad_u64_u32 v[82:83], s[78:79], s80, v82, 0
	v_mul_lo_u32 v92, s80, v91
	v_mul_lo_u32 v93, s81, v90
	v_mad_u64_u32 v[90:91], s[78:79], s80, v90, 0
	v_mul_lo_u32 v100, s80, v99
	v_mul_lo_u32 v101, s81, v98
	v_mad_u64_u32 v[98:99], s[78:79], s80, v98, 0
	v_mul_lo_u32 v108, s80, v107
	v_mul_lo_u32 v109, s81, v106
	v_mad_u64_u32 v[106:107], s[78:79], s80, v106, 0
	v_mul_lo_u32 v116, s80, v115
	v_mul_lo_u32 v117, s81, v114
	v_mad_u64_u32 v[114:115], s[78:79], s80, v114, 0
	v_mul_lo_u32 v124, s80, v123
	v_mul_lo_u32 v125, s81, v122
	v_mad_u64_u32 v[122:123], s[78:79], s80, v122, 0
	s_ashr_i32 s69, s68, 31
	v_add3_u32 v67, v67, v68, v69
	v_add3_u32 v75, v75, v76, v77
	v_add3_u32 v83, v83, v84, v85
	v_add3_u32 v91, v91, v92, v93
	v_add3_u32 v99, v99, v100, v101
	v_add3_u32 v107, v107, v108, v109
	v_add3_u32 v115, v115, v116, v117
	v_add3_u32 v123, v123, v124, v125
	v_lshl_add_u64 v[64:65], v[64:65], 2, s[28:29]
	s_lshl_b64 s[82:83], s[68:69], 2
	v_lshl_add_u64 v[66:67], v[66:67], 2, s[28:29]
	v_lshl_add_u64 v[72:73], v[72:73], 2, s[28:29]
	v_lshl_add_u64 v[74:75], v[74:75], 2, s[28:29]
	v_lshl_add_u64 v[80:81], v[80:81], 2, s[28:29]
	v_lshl_add_u64 v[82:83], v[82:83], 2, s[28:29]
	v_lshl_add_u64 v[88:89], v[88:89], 2, s[28:29]
	v_lshl_add_u64 v[90:91], v[90:91], 2, s[28:29]
	v_lshl_add_u64 v[96:97], v[96:97], 2, s[28:29]
	v_lshl_add_u64 v[98:99], v[98:99], 2, s[28:29]
	v_lshl_add_u64 v[104:105], v[104:105], 2, s[28:29]
	v_lshl_add_u64 v[106:107], v[106:107], 2, s[28:29]
	v_lshl_add_u64 v[112:113], v[112:113], 2, s[28:29]
	v_lshl_add_u64 v[114:115], v[114:115], 2, s[28:29]
	v_lshl_add_u64 v[120:121], v[120:121], 2, s[28:29]
	v_lshl_add_u64 v[122:123], v[122:123], 2, s[28:29]
	v_lshl_add_u64 v[64:65], v[64:65], 0, s[82:83]
	v_lshl_add_u64 v[66:67], v[66:67], 0, s[82:83]
	v_lshl_add_u64 v[72:73], v[72:73], 0, s[82:83]
	v_lshl_add_u64 v[74:75], v[74:75], 0, s[82:83]
	v_lshl_add_u64 v[80:81], v[80:81], 0, s[82:83]
	v_lshl_add_u64 v[82:83], v[82:83], 0, s[82:83]
	v_lshl_add_u64 v[88:89], v[88:89], 0, s[82:83]
	v_lshl_add_u64 v[90:91], v[90:91], 0, s[82:83]
	v_lshl_add_u64 v[96:97], v[96:97], 0, s[82:83]
	v_lshl_add_u64 v[98:99], v[98:99], 0, s[82:83]
	v_lshl_add_u64 v[104:105], v[104:105], 0, s[82:83]
	v_lshl_add_u64 v[106:107], v[106:107], 0, s[82:83]
	v_lshl_add_u64 v[112:113], v[112:113], 0, s[82:83]
	v_lshl_add_u64 v[114:115], v[114:115], 0, s[82:83]
	v_lshl_add_u64 v[120:121], v[120:121], 0, s[82:83]
	v_lshl_add_u64 v[122:123], v[122:123], 0, s[82:83]
	v_lshl_add_u64 v[64:65], v[64:65], 0, v[128:129]
	v_lshl_add_u64 v[68:69], v[66:67], 0, v[128:129]
	v_lshl_add_u64 v[72:73], v[72:73], 0, v[128:129]
	v_lshl_add_u64 v[76:77], v[74:75], 0, v[128:129]
	v_lshl_add_u64 v[80:81], v[80:81], 0, v[128:129]
	v_lshl_add_u64 v[84:85], v[82:83], 0, v[128:129]
	v_lshl_add_u64 v[88:89], v[88:89], 0, v[128:129]
	v_lshl_add_u64 v[92:93], v[90:91], 0, v[128:129]
	v_lshl_add_u64 v[96:97], v[96:97], 0, v[128:129]
	v_lshl_add_u64 v[100:101], v[98:99], 0, v[128:129]
	v_lshl_add_u64 v[104:105], v[104:105], 0, v[128:129]
	v_lshl_add_u64 v[108:109], v[106:107], 0, v[128:129]
	v_lshl_add_u64 v[112:113], v[112:113], 0, v[128:129]
	v_lshl_add_u64 v[116:117], v[114:115], 0, v[128:129]
	v_lshl_add_u64 v[120:121], v[120:121], 0, v[128:129]
	v_lshl_add_u64 v[124:125], v[122:123], 0, v[128:129]
	global_load_dwordx4 v[64:67], v[64:65], off nt
	s_nop 0
	global_load_dwordx4 v[68:71], v[68:69], off nt
	s_nop 0
	global_load_dwordx4 v[72:75], v[72:73], off nt
	s_nop 0
	global_load_dwordx4 v[76:79], v[76:77], off nt
	s_nop 0
	global_load_dwordx4 v[80:83], v[80:81], off nt
	s_nop 0
	global_load_dwordx4 v[84:87], v[84:85], off nt
	s_nop 0
	global_load_dwordx4 v[88:91], v[88:89], off nt
	s_nop 0
	global_load_dwordx4 v[92:95], v[92:93], off nt
	s_nop 0
	global_load_dwordx4 v[96:99], v[96:97], off nt
	s_nop 0
	global_load_dwordx4 v[100:103], v[100:101], off nt
	s_nop 0
	global_load_dwordx4 v[104:107], v[104:105], off nt
	s_nop 0
	global_load_dwordx4 v[108:111], v[108:109], off nt
	s_nop 0
	global_load_dwordx4 v[112:115], v[112:113], off nt
	s_nop 0
	global_load_dwordx4 v[116:119], v[116:117], off nt
	s_nop 0
	global_load_dwordx4 v[120:123], v[120:121], off nt
	s_nop 0
	global_load_dwordx4 v[124:127], v[124:125], off nt
	s_waitcnt vmcnt(30)
	v_cvt_pk_bf16_f32 v0, v0, v4
	v_cvt_pk_bf16_f32 v1, v1, v5
	ds_write2_b32 v150, v0, v1 offset1:32
	v_cvt_pk_bf16_f32 v0, v2, v6
	v_cvt_pk_bf16_f32 v1, v3, v7
	ds_write2_b32 v150, v0, v1 offset0:64 offset1:96
	s_waitcnt vmcnt(28)
	v_cvt_pk_bf16_f32 v0, v8, v12
	v_cvt_pk_bf16_f32 v1, v9, v13
	ds_write2_b32 v151, v0, v1 offset1:32
	v_cvt_pk_bf16_f32 v0, v10, v14
	v_cvt_pk_bf16_f32 v1, v11, v15
	ds_write2_b32 v151, v0, v1 offset0:64 offset1:96
	s_waitcnt vmcnt(26)
	v_cvt_pk_bf16_f32 v0, v16, v20
	v_cvt_pk_bf16_f32 v1, v17, v21
	ds_write2_b32 v152, v0, v1 offset1:32
	v_cvt_pk_bf16_f32 v0, v18, v22
	v_cvt_pk_bf16_f32 v1, v19, v23
	ds_write2_b32 v152, v0, v1 offset0:64 offset1:96
	s_waitcnt vmcnt(24)
	v_cvt_pk_bf16_f32 v0, v24, v28
	v_cvt_pk_bf16_f32 v1, v25, v29
	ds_write2_b32 v153, v0, v1 offset1:32
	v_cvt_pk_bf16_f32 v0, v26, v30
	v_cvt_pk_bf16_f32 v1, v27, v31
	ds_write2_b32 v153, v0, v1 offset0:64 offset1:96
	s_waitcnt vmcnt(22)
	v_cvt_pk_bf16_f32 v0, v32, v36
	v_cvt_pk_bf16_f32 v1, v33, v37
	ds_write2_b32 v154, v0, v1 offset1:32
	v_cvt_pk_bf16_f32 v0, v34, v38
	v_cvt_pk_bf16_f32 v1, v35, v39
	ds_write2_b32 v154, v0, v1 offset0:64 offset1:96
	s_waitcnt vmcnt(20)
	v_cvt_pk_bf16_f32 v0, v40, v44
	v_cvt_pk_bf16_f32 v1, v41, v45
	ds_write2_b32 v155, v0, v1 offset1:32
	v_cvt_pk_bf16_f32 v0, v42, v46
	v_cvt_pk_bf16_f32 v1, v43, v47
	ds_write2_b32 v155, v0, v1 offset0:64 offset1:96
	s_waitcnt vmcnt(18)
	v_cvt_pk_bf16_f32 v0, v48, v52
	v_cvt_pk_bf16_f32 v1, v49, v53
	ds_write2_b32 v156, v0, v1 offset1:32
	v_cvt_pk_bf16_f32 v0, v50, v54
	v_cvt_pk_bf16_f32 v1, v51, v55
	ds_write2_b32 v156, v0, v1 offset0:64 offset1:96
	s_waitcnt vmcnt(16)
	v_cvt_pk_bf16_f32 v0, v56, v60
	v_cvt_pk_bf16_f32 v1, v57, v61
	ds_write2_b32 v157, v0, v1 offset1:32
	v_cvt_pk_bf16_f32 v0, v58, v62
	v_cvt_pk_bf16_f32 v1, v59, v63
	ds_write2_b32 v157, v0, v1 offset0:64 offset1:96
	s_waitcnt lgkmcnt(0)
	ds_read_b128 v[24:27], v136
	ds_read_b128 v[20:23], v138
	ds_read_b128 v[16:19], v140
	ds_read_b128 v[12:15], v142
	ds_read_b128 v[8:11], v144
	ds_read_b128 v[4:7], v146
	ds_read_b128 v[0:3], v148
	v_lshlrev_b32_e32 v28, 6, v132
	v_ashrrev_i32_e32 v29, 31, v28
	v_lshlrev_b32_e32 v132, 1, v130
	s_and_saveexec_b64 s[28:29], s[0:1]
	s_cbranch_execnz .LBB8_321
	s_or_b64 exec, exec, s[28:29]
	s_and_saveexec_b64 s[28:29], s[16:17]
	s_cbranch_execnz .LBB8_322

.LBB8_338:
	v_lshl_add_u32 v58, s69, 6, v134
	s_waitcnt lgkmcnt(2)
	v_add_u32_e32 v8, 8, v58
	v_add_u32_e32 v16, 16, v58
	v_add_u32_e32 v24, 24, v58
	v_add_u32_e32 v32, 32, v58
	v_add_u32_e32 v40, 40, v58
	v_add_u32_e32 v48, 48, v58
	s_waitcnt lgkmcnt(0)
	v_ashrrev_i32_e32 v0, 31, v58
	v_ashrrev_i32_e32 v9, 31, v8
	v_ashrrev_i32_e32 v17, 31, v16
	v_ashrrev_i32_e32 v25, 31, v24
	v_ashrrev_i32_e32 v33, 31, v32
	v_ashrrev_i32_e32 v41, 31, v40
	v_ashrrev_i32_e32 v49, 31, v48
	v_add_u32_e32 v56, 56, v58
	v_mul_lo_u32 v4, s76, v0
	v_mul_lo_u32 v2, s77, v58
	v_mad_u64_u32 v[0:1], s[78:79], s76, v58, 0
	v_mul_lo_u32 v10, s76, v9
	v_mul_lo_u32 v11, s77, v8
	v_mad_u64_u32 v[8:9], s[78:79], s76, v8, 0
	v_mul_lo_u32 v18, s76, v17
	v_mul_lo_u32 v19, s77, v16
	v_mad_u64_u32 v[16:17], s[78:79], s76, v16, 0
	v_mul_lo_u32 v26, s76, v25
	v_mul_lo_u32 v27, s77, v24
	v_mad_u64_u32 v[24:25], s[78:79], s76, v24, 0
	v_mul_lo_u32 v34, s76, v33
	v_mul_lo_u32 v35, s77, v32
	v_mad_u64_u32 v[32:33], s[78:79], s76, v32, 0
	v_mul_lo_u32 v42, s76, v41
	v_mul_lo_u32 v43, s77, v40
	v_mad_u64_u32 v[40:41], s[78:79], s76, v40, 0
	v_mul_lo_u32 v50, s76, v49
	v_mul_lo_u32 v51, s77, v48
	v_mad_u64_u32 v[48:49], s[78:79], s76, v48, 0
	v_ashrrev_i32_e32 v57, 31, v56
	v_add3_u32 v1, v1, v4, v2
	v_or_b32_e32 v2, 1, v58
	v_add3_u32 v9, v9, v10, v11
	v_add_u32_e32 v10, 9, v58
	v_add3_u32 v17, v17, v18, v19
	v_add_u32_e32 v18, 17, v58
	v_add3_u32 v25, v25, v26, v27
	v_add_u32_e32 v26, 25, v58
	v_add3_u32 v33, v33, v34, v35
	v_add_u32_e32 v34, 33, v58
	v_add3_u32 v41, v41, v42, v43
	v_add_u32_e32 v42, 41, v58
	v_add3_u32 v49, v49, v50, v51
	v_add_u32_e32 v50, 49, v58
	v_mul_lo_u32 v59, s76, v57
	v_mul_lo_u32 v60, s77, v56
	v_mad_u64_u32 v[56:57], s[78:79], s76, v56, 0
	v_add_u32_e32 v58, 57, v58
	v_ashrrev_i32_e32 v11, 31, v10
	v_ashrrev_i32_e32 v19, 31, v18
	v_ashrrev_i32_e32 v27, 31, v26
	v_ashrrev_i32_e32 v35, 31, v34
	v_ashrrev_i32_e32 v43, 31, v42
	v_ashrrev_i32_e32 v51, 31, v50
	v_add3_u32 v57, v57, v59, v60
	v_ashrrev_i32_e32 v59, 31, v58
	v_mul_lo_u32 v5, s77, v2
	v_mad_u64_u32 v[2:3], s[78:79], s76, v2, 0
	v_mul_lo_u32 v12, s76, v11
	v_mul_lo_u32 v13, s77, v10
	v_mad_u64_u32 v[10:11], s[78:79], s76, v10, 0
	v_mul_lo_u32 v20, s76, v19
	v_mul_lo_u32 v21, s77, v18
	v_mad_u64_u32 v[18:19], s[78:79], s76, v18, 0
	v_mul_lo_u32 v28, s76, v27
	v_mul_lo_u32 v29, s77, v26
	v_mad_u64_u32 v[26:27], s[78:79], s76, v26, 0
	v_mul_lo_u32 v36, s76, v35
	v_mul_lo_u32 v37, s77, v34
	v_mad_u64_u32 v[34:35], s[78:79], s76, v34, 0
	v_mul_lo_u32 v44, s76, v43
	v_mul_lo_u32 v45, s77, v42
	v_mad_u64_u32 v[42:43], s[78:79], s76, v42, 0
	v_mul_lo_u32 v52, s76, v51
	v_mul_lo_u32 v53, s77, v50
	v_mad_u64_u32 v[50:51], s[78:79], s76, v50, 0
	v_mul_lo_u32 v60, s76, v59
	v_mul_lo_u32 v61, s77, v58
	v_mad_u64_u32 v[58:59], s[76:77], s76, v58, 0
	s_ashr_i32 s61, s60, 31
	v_add3_u32 v3, v3, v4, v5
	v_add3_u32 v11, v11, v12, v13
	v_add3_u32 v19, v19, v20, v21
	v_add3_u32 v27, v27, v28, v29
	v_add3_u32 v35, v35, v36, v37
	v_add3_u32 v43, v43, v44, v45
	v_add3_u32 v51, v51, v52, v53
	v_add3_u32 v59, v59, v60, v61
	v_lshl_add_u64 v[0:1], v[0:1], 2, s[28:29]
	s_lshl_b64 s[80:81], s[60:61], 2
	v_lshl_add_u64 v[2:3], v[2:3], 2, s[28:29]
	v_lshl_add_u64 v[8:9], v[8:9], 2, s[28:29]
	v_lshl_add_u64 v[10:11], v[10:11], 2, s[28:29]
	v_lshl_add_u64 v[16:17], v[16:17], 2, s[28:29]
	v_lshl_add_u64 v[18:19], v[18:19], 2, s[28:29]
	v_lshl_add_u64 v[24:25], v[24:25], 2, s[28:29]
	v_lshl_add_u64 v[26:27], v[26:27], 2, s[28:29]
	v_lshl_add_u64 v[32:33], v[32:33], 2, s[28:29]
	v_lshl_add_u64 v[34:35], v[34:35], 2, s[28:29]
	v_lshl_add_u64 v[40:41], v[40:41], 2, s[28:29]
	v_lshl_add_u64 v[42:43], v[42:43], 2, s[28:29]
	v_lshl_add_u64 v[48:49], v[48:49], 2, s[28:29]
	v_lshl_add_u64 v[50:51], v[50:51], 2, s[28:29]
	v_lshl_add_u64 v[56:57], v[56:57], 2, s[28:29]
	v_lshl_add_u64 v[58:59], v[58:59], 2, s[28:29]
	v_lshl_add_u64 v[0:1], v[0:1], 0, s[80:81]
	v_lshl_add_u64 v[2:3], v[2:3], 0, s[80:81]
	v_lshl_add_u64 v[8:9], v[8:9], 0, s[80:81]
	v_lshl_add_u64 v[10:11], v[10:11], 0, s[80:81]
	v_lshl_add_u64 v[16:17], v[16:17], 0, s[80:81]
	v_lshl_add_u64 v[18:19], v[18:19], 0, s[80:81]
	v_lshl_add_u64 v[24:25], v[24:25], 0, s[80:81]
	v_lshl_add_u64 v[26:27], v[26:27], 0, s[80:81]
	v_lshl_add_u64 v[32:33], v[32:33], 0, s[80:81]
	v_lshl_add_u64 v[34:35], v[34:35], 0, s[80:81]
	v_lshl_add_u64 v[40:41], v[40:41], 0, s[80:81]
	v_lshl_add_u64 v[42:43], v[42:43], 0, s[80:81]
	v_lshl_add_u64 v[48:49], v[48:49], 0, s[80:81]
	v_lshl_add_u64 v[50:51], v[50:51], 0, s[80:81]
	v_lshl_add_u64 v[56:57], v[56:57], 0, s[80:81]
	v_lshl_add_u64 v[58:59], v[58:59], 0, s[80:81]
	v_lshl_add_u64 v[0:1], v[0:1], 0, v[128:129]
	v_lshl_add_u64 v[4:5], v[2:3], 0, v[128:129]
	v_lshl_add_u64 v[8:9], v[8:9], 0, v[128:129]
	v_lshl_add_u64 v[12:13], v[10:11], 0, v[128:129]
	v_lshl_add_u64 v[16:17], v[16:17], 0, v[128:129]
	v_lshl_add_u64 v[20:21], v[18:19], 0, v[128:129]
	v_lshl_add_u64 v[24:25], v[24:25], 0, v[128:129]
	v_lshl_add_u64 v[28:29], v[26:27], 0, v[128:129]
	v_lshl_add_u64 v[32:33], v[32:33], 0, v[128:129]
	v_lshl_add_u64 v[36:37], v[34:35], 0, v[128:129]
	v_lshl_add_u64 v[40:41], v[40:41], 0, v[128:129]
	v_lshl_add_u64 v[44:45], v[42:43], 0, v[128:129]
	v_lshl_add_u64 v[48:49], v[48:49], 0, v[128:129]
	v_lshl_add_u64 v[52:53], v[50:51], 0, v[128:129]
	v_lshl_add_u64 v[56:57], v[56:57], 0, v[128:129]
	v_lshl_add_u64 v[60:61], v[58:59], 0, v[128:129]
	global_load_dwordx4 v[0:3], v[0:1], off nt
	s_nop 0
	global_load_dwordx4 v[4:7], v[4:5], off nt
	s_nop 0
	global_load_dwordx4 v[8:11], v[8:9], off nt
	s_nop 0
	global_load_dwordx4 v[12:15], v[12:13], off nt
	s_nop 0
	global_load_dwordx4 v[16:19], v[16:17], off nt
	s_nop 0
	global_load_dwordx4 v[20:23], v[20:21], off nt
	s_nop 0
	global_load_dwordx4 v[24:27], v[24:25], off nt
	s_nop 0
	global_load_dwordx4 v[28:31], v[28:29], off nt
	s_nop 0
	global_load_dwordx4 v[32:35], v[32:33], off nt
	s_nop 0
	global_load_dwordx4 v[36:39], v[36:37], off nt
	s_nop 0
	global_load_dwordx4 v[40:43], v[40:41], off nt
	s_nop 0
	global_load_dwordx4 v[44:47], v[44:45], off nt
	s_nop 0
	global_load_dwordx4 v[48:51], v[48:49], off nt
	s_nop 0
	global_load_dwordx4 v[52:55], v[52:53], off nt
	s_nop 0
	global_load_dwordx4 v[56:59], v[56:57], off nt
	s_nop 0
	global_load_dwordx4 v[60:63], v[60:61], off nt
	s_waitcnt vmcnt(30)
	v_cvt_pk_bf16_f32 v64, v64, v68
	v_cvt_pk_bf16_f32 v65, v65, v69
	ds_write2_b32 v150, v64, v65 offset1:32
	v_cvt_pk_bf16_f32 v64, v66, v70
	v_cvt_pk_bf16_f32 v65, v67, v71
	ds_write2_b32 v150, v64, v65 offset0:64 offset1:96
	s_waitcnt vmcnt(28)
	v_cvt_pk_bf16_f32 v64, v72, v76
	v_cvt_pk_bf16_f32 v65, v73, v77
	ds_write2_b32 v151, v64, v65 offset1:32
	v_cvt_pk_bf16_f32 v64, v74, v78
	v_cvt_pk_bf16_f32 v65, v75, v79
	ds_write2_b32 v151, v64, v65 offset0:64 offset1:96
	s_waitcnt vmcnt(26)
	v_cvt_pk_bf16_f32 v64, v80, v84
	v_cvt_pk_bf16_f32 v65, v81, v85
	ds_write2_b32 v152, v64, v65 offset1:32
	v_cvt_pk_bf16_f32 v64, v82, v86
	v_cvt_pk_bf16_f32 v65, v83, v87
	ds_write2_b32 v152, v64, v65 offset0:64 offset1:96
	s_waitcnt vmcnt(24)
	v_cvt_pk_bf16_f32 v64, v88, v92
	v_cvt_pk_bf16_f32 v65, v89, v93
	ds_write2_b32 v153, v64, v65 offset1:32
	v_cvt_pk_bf16_f32 v64, v90, v94
	v_cvt_pk_bf16_f32 v65, v91, v95
	ds_write2_b32 v153, v64, v65 offset0:64 offset1:96
	s_waitcnt vmcnt(22)
	v_cvt_pk_bf16_f32 v64, v96, v100
	v_cvt_pk_bf16_f32 v65, v97, v101
	ds_write2_b32 v154, v64, v65 offset1:32
	v_cvt_pk_bf16_f32 v64, v98, v102
	v_cvt_pk_bf16_f32 v65, v99, v103
	ds_write2_b32 v154, v64, v65 offset0:64 offset1:96
	s_waitcnt vmcnt(20)
	v_cvt_pk_bf16_f32 v64, v104, v108
	v_cvt_pk_bf16_f32 v65, v105, v109
	ds_write2_b32 v155, v64, v65 offset1:32
	v_cvt_pk_bf16_f32 v64, v106, v110
	v_cvt_pk_bf16_f32 v65, v107, v111
	ds_write2_b32 v155, v64, v65 offset0:64 offset1:96
	s_waitcnt vmcnt(18)
	v_cvt_pk_bf16_f32 v64, v112, v116
	v_cvt_pk_bf16_f32 v65, v113, v117
	ds_write2_b32 v156, v64, v65 offset1:32
	v_cvt_pk_bf16_f32 v64, v114, v118
	v_cvt_pk_bf16_f32 v65, v115, v119
	ds_write2_b32 v156, v64, v65 offset0:64 offset1:96
	s_waitcnt vmcnt(16)
	v_cvt_pk_bf16_f32 v64, v120, v124
	v_cvt_pk_bf16_f32 v65, v121, v125
	ds_write2_b32 v157, v64, v65 offset1:32
	v_cvt_pk_bf16_f32 v64, v122, v126
	v_cvt_pk_bf16_f32 v65, v123, v127
	ds_write2_b32 v157, v64, v65 offset0:64 offset1:96
	s_waitcnt lgkmcnt(0)
	ds_read_b128 v[88:91], v136
	ds_read_b128 v[84:87], v138
	ds_read_b128 v[80:83], v140
	ds_read_b128 v[76:79], v142
	ds_read_b128 v[72:75], v144
	ds_read_b128 v[68:71], v146
	ds_read_b128 v[64:67], v148
	s_ashr_i32 s75, s74, 31
	s_and_saveexec_b64 s[28:29], s[0:1]
	s_cbranch_execnz .LBB8_346
	s_or_b64 exec, exec, s[28:29]
	s_and_saveexec_b64 s[28:29], s[16:17]
	s_cbranch_execnz .LBB8_347

.LBB8_716:
	s_lshl_b32 s76, s80, 6
	s_waitcnt vmcnt(0)
	v_add_u32_e32 v38, s76, v161
	v_ashrrev_i32_e32 v0, 31, v38
	v_mul_lo_u32 v39, s84, v0
	v_mul_lo_u32 v0, s85, v38
	v_mad_u64_u32 v[34:35], s[80:81], s84, v38, 0
	v_or_b32_e32 v36, 1, v38
	v_add3_u32 v35, v35, v39, v0
	s_ashr_i32 s69, s68, 31
	v_mul_lo_u32 v40, s85, v36
	v_mad_u64_u32 v[36:37], vcc, s84, v36, 0
	v_lshl_add_u64 v[34:35], v[34:35], 2, s[28:29]
	s_lshl_b64 s[80:81], s[68:69], 2
	v_add3_u32 v37, v37, v39, v40
	v_lshl_add_u64 v[34:35], v[34:35], 0, s[80:81]
	v_lshlrev_b32_e32 v0, 2, v158
	v_lshl_add_u64 v[36:37], v[36:37], 2, s[28:29]
	v_lshl_add_u64 v[34:35], v[34:35], 0, v[0:1]
	v_lshl_add_u64 v[36:37], v[36:37], 0, s[80:81]
	v_lshl_add_u64 v[36:37], v[36:37], 0, v[0:1]
	global_load_dwordx4 v[122:125], v[34:35], off nt
	global_load_dwordx4 v[126:129], v[36:37], off nt
	v_add_u32_e32 v34, 8, v38
	v_ashrrev_i32_e32 v35, 31, v34
	v_mul_lo_u32 v36, s84, v35
	v_mul_lo_u32 v37, s85, v34
	v_mad_u64_u32 v[34:35], vcc, s84, v34, 0
	v_add3_u32 v35, v35, v36, v37
	v_add_u32_e32 v36, 9, v38
	v_ashrrev_i32_e32 v37, 31, v36
	v_mul_lo_u32 v39, s84, v37
	v_mul_lo_u32 v40, s85, v36
	v_mad_u64_u32 v[36:37], vcc, s84, v36, 0
	v_lshl_add_u64 v[34:35], v[34:35], 2, s[28:29]
	v_add3_u32 v37, v37, v39, v40
	v_lshl_add_u64 v[34:35], v[34:35], 0, s[80:81]
	v_lshl_add_u64 v[36:37], v[36:37], 2, s[28:29]
	v_lshl_add_u64 v[34:35], v[34:35], 0, v[0:1]
	v_lshl_add_u64 v[36:37], v[36:37], 0, s[80:81]
	v_lshl_add_u64 v[36:37], v[36:37], 0, v[0:1]
	global_load_dwordx4 v[114:117], v[34:35], off nt
	global_load_dwordx4 v[118:121], v[36:37], off nt
	v_add_u32_e32 v34, 16, v38
	v_ashrrev_i32_e32 v35, 31, v34
	v_mul_lo_u32 v36, s84, v35
	v_mul_lo_u32 v37, s85, v34
	v_mad_u64_u32 v[34:35], vcc, s84, v34, 0
	v_add3_u32 v35, v35, v36, v37
	v_add_u32_e32 v36, 17, v38
	v_ashrrev_i32_e32 v37, 31, v36
	v_mul_lo_u32 v39, s84, v37
	v_mul_lo_u32 v40, s85, v36
	v_mad_u64_u32 v[36:37], vcc, s84, v36, 0
	v_lshl_add_u64 v[34:35], v[34:35], 2, s[28:29]
	v_add3_u32 v37, v37, v39, v40
	v_lshl_add_u64 v[34:35], v[34:35], 0, s[80:81]
	v_lshl_add_u64 v[36:37], v[36:37], 2, s[28:29]
	v_lshl_add_u64 v[34:35], v[34:35], 0, v[0:1]
	v_lshl_add_u64 v[36:37], v[36:37], 0, s[80:81]
	v_lshl_add_u64 v[36:37], v[36:37], 0, v[0:1]
	global_load_dwordx4 v[106:109], v[34:35], off nt
	global_load_dwordx4 v[110:113], v[36:37], off nt
	v_add_u32_e32 v34, 24, v38
	v_ashrrev_i32_e32 v35, 31, v34
	v_mul_lo_u32 v36, s84, v35
	v_mul_lo_u32 v37, s85, v34
	v_mad_u64_u32 v[34:35], vcc, s84, v34, 0
	v_add3_u32 v35, v35, v36, v37
	v_add_u32_e32 v36, 25, v38
	v_ashrrev_i32_e32 v37, 31, v36
	v_mul_lo_u32 v39, s84, v37
	v_mul_lo_u32 v40, s85, v36
	v_mad_u64_u32 v[36:37], vcc, s84, v36, 0
	v_lshl_add_u64 v[34:35], v[34:35], 2, s[28:29]
	v_add3_u32 v37, v37, v39, v40
	v_lshl_add_u64 v[34:35], v[34:35], 0, s[80:81]
	v_lshl_add_u64 v[36:37], v[36:37], 2, s[28:29]
	v_lshl_add_u64 v[34:35], v[34:35], 0, v[0:1]
	v_lshl_add_u64 v[36:37], v[36:37], 0, s[80:81]
	v_lshl_add_u64 v[36:37], v[36:37], 0, v[0:1]
	global_load_dwordx4 v[98:101], v[34:35], off nt
	global_load_dwordx4 v[102:105], v[36:37], off nt
	v_add_u32_e32 v34, 32, v38
	v_ashrrev_i32_e32 v35, 31, v34
	v_mul_lo_u32 v36, s84, v35
	v_mul_lo_u32 v37, s85, v34
	v_mad_u64_u32 v[34:35], vcc, s84, v34, 0
	v_add3_u32 v35, v35, v36, v37
	v_add_u32_e32 v36, 33, v38
	v_ashrrev_i32_e32 v37, 31, v36
	v_mul_lo_u32 v39, s84, v37
	v_mul_lo_u32 v40, s85, v36
	v_mad_u64_u32 v[36:37], vcc, s84, v36, 0
	v_lshl_add_u64 v[34:35], v[34:35], 2, s[28:29]
	v_add3_u32 v37, v37, v39, v40
	v_lshl_add_u64 v[34:35], v[34:35], 0, s[80:81]
	v_lshl_add_u64 v[36:37], v[36:37], 2, s[28:29]
	v_lshl_add_u64 v[34:35], v[34:35], 0, v[0:1]
	v_lshl_add_u64 v[36:37], v[36:37], 0, s[80:81]
	v_lshl_add_u64 v[36:37], v[36:37], 0, v[0:1]
	global_load_dwordx4 v[74:77], v[34:35], off nt
	global_load_dwordx4 v[78:81], v[36:37], off nt
	v_add_u32_e32 v34, 40, v38
	v_ashrrev_i32_e32 v35, 31, v34
	v_mul_lo_u32 v36, s84, v35
	v_mul_lo_u32 v37, s85, v34
	v_mad_u64_u32 v[34:35], vcc, s84, v34, 0
	v_add3_u32 v35, v35, v36, v37
	v_add_u32_e32 v36, 41, v38
	v_ashrrev_i32_e32 v37, 31, v36
	v_mul_lo_u32 v39, s84, v37
	v_mul_lo_u32 v40, s85, v36
	v_mad_u64_u32 v[36:37], vcc, s84, v36, 0
	v_lshl_add_u64 v[34:35], v[34:35], 2, s[28:29]
	v_add3_u32 v37, v37, v39, v40
	v_lshl_add_u64 v[34:35], v[34:35], 0, s[80:81]
	v_lshl_add_u64 v[36:37], v[36:37], 2, s[28:29]
	v_lshl_add_u64 v[34:35], v[34:35], 0, v[0:1]
	v_lshl_add_u64 v[36:37], v[36:37], 0, s[80:81]
	v_lshl_add_u64 v[36:37], v[36:37], 0, v[0:1]
	global_load_dwordx4 v[66:69], v[34:35], off nt
	global_load_dwordx4 v[70:73], v[36:37], off nt
	v_add_u32_e32 v34, 48, v38
	v_ashrrev_i32_e32 v35, 31, v34
	v_mul_lo_u32 v36, s84, v35
	v_mul_lo_u32 v37, s85, v34
	v_mad_u64_u32 v[34:35], vcc, s84, v34, 0
	v_add3_u32 v35, v35, v36, v37
	v_add_u32_e32 v36, 49, v38
	v_ashrrev_i32_e32 v37, 31, v36
	v_mul_lo_u32 v39, s84, v37
	v_mul_lo_u32 v40, s85, v36
	v_mad_u64_u32 v[36:37], vcc, s84, v36, 0
	v_lshl_add_u64 v[34:35], v[34:35], 2, s[28:29]
	v_add3_u32 v37, v37, v39, v40
	v_lshl_add_u64 v[34:35], v[34:35], 0, s[80:81]
	v_lshl_add_u64 v[36:37], v[36:37], 2, s[28:29]
	v_lshl_add_u64 v[34:35], v[34:35], 0, v[0:1]
	v_lshl_add_u64 v[36:37], v[36:37], 0, s[80:81]
	v_lshl_add_u64 v[36:37], v[36:37], 0, v[0:1]
	global_load_dwordx4 v[42:45], v[34:35], off nt
	global_load_dwordx4 v[46:49], v[36:37], off nt
	v_add_u32_e32 v34, 56, v38
	v_ashrrev_i32_e32 v35, 31, v34
	v_mul_lo_u32 v36, s84, v35
	v_mul_lo_u32 v37, s85, v34
	v_mad_u64_u32 v[34:35], vcc, s84, v34, 0
	v_add3_u32 v35, v35, v36, v37
	v_add_u32_e32 v36, 57, v38
	v_ashrrev_i32_e32 v37, 31, v36
	v_mul_lo_u32 v38, s84, v37
	v_mul_lo_u32 v39, s85, v36
	v_mad_u64_u32 v[36:37], s[84:85], s84, v36, 0
	v_add3_u32 v37, v37, v38, v39
	v_lshl_add_u64 v[34:35], v[34:35], 2, s[28:29]
	v_lshl_add_u64 v[36:37], v[36:37], 2, s[28:29]
	v_lshl_add_u64 v[34:35], v[34:35], 0, s[80:81]
	v_lshl_add_u64 v[36:37], v[36:37], 0, s[80:81]
	v_lshl_add_u64 v[34:35], v[34:35], 0, v[0:1]
	v_lshl_add_u64 v[38:39], v[36:37], 0, v[0:1]
	global_load_dwordx4 v[34:37], v[34:35], off nt
	s_nop 0
	global_load_dwordx4 v[38:41], v[38:39], off nt
	s_waitcnt vmcnt(30) lgkmcnt(0)
	v_cvt_pk_bf16_f32 v130, v90, v94
	v_cvt_pk_bf16_f32 v131, v91, v95
	ds_write2_b32 v191, v130, v131 offset1:32
	v_cvt_pk_bf16_f32 v130, v92, v96
	v_cvt_pk_bf16_f32 v131, v93, v97
	ds_write2_b32 v191, v130, v131 offset0:64 offset1:96
	s_waitcnt vmcnt(28)
	v_cvt_pk_bf16_f32 v130, v82, v86
	v_cvt_pk_bf16_f32 v131, v83, v87
	ds_write2_b32 v192, v130, v131 offset1:32
	v_cvt_pk_bf16_f32 v130, v84, v88
	v_cvt_pk_bf16_f32 v131, v85, v89
	ds_write2_b32 v192, v130, v131 offset0:64 offset1:96
	s_waitcnt vmcnt(26)
	v_cvt_pk_bf16_f32 v130, v58, v62
	v_cvt_pk_bf16_f32 v131, v59, v63
	ds_write2_b32 v193, v130, v131 offset1:32
	v_cvt_pk_bf16_f32 v130, v60, v64
	v_cvt_pk_bf16_f32 v131, v61, v65
	ds_write2_b32 v193, v130, v131 offset0:64 offset1:96
	s_waitcnt vmcnt(24)
	v_cvt_pk_bf16_f32 v130, v50, v54
	v_cvt_pk_bf16_f32 v131, v51, v55
	ds_write2_b32 v194, v130, v131 offset1:32
	v_cvt_pk_bf16_f32 v130, v52, v56
	v_cvt_pk_bf16_f32 v131, v53, v57
	ds_write2_b32 v194, v130, v131 offset0:64 offset1:96
	s_waitcnt vmcnt(22)
	v_cvt_pk_bf16_f32 v130, v26, v30
	v_cvt_pk_bf16_f32 v131, v27, v31
	ds_write2_b32 v195, v130, v131 offset1:32
	v_cvt_pk_bf16_f32 v130, v28, v32
	v_cvt_pk_bf16_f32 v131, v29, v33
	ds_write2_b32 v195, v130, v131 offset0:64 offset1:96
	s_waitcnt vmcnt(20)
	v_cvt_pk_bf16_f32 v130, v18, v22
	v_cvt_pk_bf16_f32 v131, v19, v23
	ds_write2_b32 v196, v130, v131 offset1:32
	v_cvt_pk_bf16_f32 v130, v20, v24
	v_cvt_pk_bf16_f32 v131, v21, v25
	ds_write2_b32 v196, v130, v131 offset0:64 offset1:96
	s_waitcnt vmcnt(18)
	v_cvt_pk_bf16_f32 v130, v10, v14
	v_cvt_pk_bf16_f32 v131, v11, v15
	ds_write2_b32 v197, v130, v131 offset1:32
	v_cvt_pk_bf16_f32 v130, v12, v16
	v_cvt_pk_bf16_f32 v131, v13, v17
	ds_write2_b32 v197, v130, v131 offset0:64 offset1:96
	s_waitcnt vmcnt(16)
	v_cvt_pk_bf16_f32 v130, v2, v6
	v_cvt_pk_bf16_f32 v131, v3, v7
	ds_write2_b32 v198, v130, v131 offset1:32
	v_cvt_pk_bf16_f32 v130, v4, v8
	v_cvt_pk_bf16_f32 v131, v5, v9
	ds_write2_b32 v198, v130, v131 offset0:64 offset1:96
	s_waitcnt lgkmcnt(0)
	ds_read_b128 v[154:157], v176
	ds_read_b128 v[150:153], v178
	ds_read_b128 v[146:149], v180
	ds_read_b128 v[142:145], v182
	ds_read_b128 v[138:141], v184
	ds_read_b128 v[134:137], v186
	ds_read_b128 v[130:133], v188
	s_lshl_b32 s28, s57, 6
	s_ashr_i32 s29, s28, 31
	v_lshlrev_b32_e32 v166, 1, v160
	s_and_saveexec_b64 s[84:85], s[22:23]
	s_cbranch_execnz .LBB8_734
	s_or_b64 exec, exec, s[84:85]
	s_and_saveexec_b64 s[84:85], s[4:5]
	s_cbranch_execnz .LBB8_735

.LBB8_751:
	v_lshl_add_u32 v6, s57, 6, v161
	v_ashrrev_i32_e32 v2, 31, v6
	v_mul_lo_u32 v7, s84, v2
	v_mul_lo_u32 v4, s85, v6
	v_mad_u64_u32 v[2:3], vcc, s84, v6, 0
	v_add3_u32 v3, v3, v7, v4
	v_or_b32_e32 v4, 1, v6
	s_ashr_i32 s97, s96, 31
	v_mul_lo_u32 v8, s85, v4
	v_mad_u64_u32 v[4:5], s[52:53], s84, v4, 0
	v_lshl_add_u64 v[2:3], v[2:3], 2, s[28:29]
	s_lshl_b64 vcc, s[96:97], 2
	v_add3_u32 v5, v5, v7, v8
	v_lshl_add_u64 v[2:3], v[2:3], 0, vcc
	v_lshl_add_u64 v[4:5], v[4:5], 2, s[28:29]
	v_lshl_add_u64 v[2:3], v[2:3], 0, v[0:1]
	v_lshl_add_u64 v[4:5], v[4:5], 0, vcc
	v_lshl_add_u64 v[4:5], v[4:5], 0, v[0:1]
	global_load_dwordx4 v[90:93], v[2:3], off nt
	global_load_dwordx4 v[94:97], v[4:5], off nt
	v_add_u32_e32 v2, 8, v6
	v_ashrrev_i32_e32 v3, 31, v2
	v_mul_lo_u32 v4, s84, v3
	v_mul_lo_u32 v5, s85, v2
	v_mad_u64_u32 v[2:3], s[52:53], s84, v2, 0
	v_add3_u32 v3, v3, v4, v5
	v_add_u32_e32 v4, 9, v6
	v_ashrrev_i32_e32 v5, 31, v4
	v_mul_lo_u32 v7, s84, v5
	v_mul_lo_u32 v8, s85, v4
	v_mad_u64_u32 v[4:5], s[52:53], s84, v4, 0
	v_lshl_add_u64 v[2:3], v[2:3], 2, s[28:29]
	v_add3_u32 v5, v5, v7, v8
	v_lshl_add_u64 v[2:3], v[2:3], 0, vcc
	v_lshl_add_u64 v[4:5], v[4:5], 2, s[28:29]
	v_lshl_add_u64 v[2:3], v[2:3], 0, v[0:1]
	v_lshl_add_u64 v[4:5], v[4:5], 0, vcc
	v_lshl_add_u64 v[4:5], v[4:5], 0, v[0:1]
	global_load_dwordx4 v[82:85], v[2:3], off nt
	global_load_dwordx4 v[86:89], v[4:5], off nt
	v_add_u32_e32 v2, 16, v6
	v_ashrrev_i32_e32 v3, 31, v2
	v_mul_lo_u32 v4, s84, v3
	v_mul_lo_u32 v5, s85, v2
	v_mad_u64_u32 v[2:3], s[52:53], s84, v2, 0
	v_add3_u32 v3, v3, v4, v5
	v_add_u32_e32 v4, 17, v6
	v_ashrrev_i32_e32 v5, 31, v4
	v_mul_lo_u32 v7, s84, v5
	v_mul_lo_u32 v8, s85, v4
	v_mad_u64_u32 v[4:5], s[52:53], s84, v4, 0
	v_lshl_add_u64 v[2:3], v[2:3], 2, s[28:29]
	v_add3_u32 v5, v5, v7, v8
	v_lshl_add_u64 v[2:3], v[2:3], 0, vcc
	v_lshl_add_u64 v[4:5], v[4:5], 2, s[28:29]
	v_lshl_add_u64 v[2:3], v[2:3], 0, v[0:1]
	v_lshl_add_u64 v[4:5], v[4:5], 0, vcc
	v_lshl_add_u64 v[4:5], v[4:5], 0, v[0:1]
	global_load_dwordx4 v[58:61], v[2:3], off nt
	global_load_dwordx4 v[62:65], v[4:5], off nt
	v_add_u32_e32 v2, 24, v6
	v_ashrrev_i32_e32 v3, 31, v2
	v_mul_lo_u32 v4, s84, v3
	v_mul_lo_u32 v5, s85, v2
	v_mad_u64_u32 v[2:3], s[52:53], s84, v2, 0
	v_add3_u32 v3, v3, v4, v5
	v_add_u32_e32 v4, 25, v6
	v_ashrrev_i32_e32 v5, 31, v4
	v_mul_lo_u32 v7, s84, v5
	v_mul_lo_u32 v8, s85, v4
	v_mad_u64_u32 v[4:5], s[52:53], s84, v4, 0
	v_lshl_add_u64 v[2:3], v[2:3], 2, s[28:29]
	v_add3_u32 v5, v5, v7, v8
	v_lshl_add_u64 v[2:3], v[2:3], 0, vcc
	v_lshl_add_u64 v[4:5], v[4:5], 2, s[28:29]
	v_lshl_add_u64 v[2:3], v[2:3], 0, v[0:1]
	v_lshl_add_u64 v[4:5], v[4:5], 0, vcc
	v_lshl_add_u64 v[4:5], v[4:5], 0, v[0:1]
	global_load_dwordx4 v[50:53], v[2:3], off nt
	global_load_dwordx4 v[54:57], v[4:5], off nt
	v_add_u32_e32 v2, 32, v6
	v_ashrrev_i32_e32 v3, 31, v2
	v_mul_lo_u32 v4, s84, v3
	v_mul_lo_u32 v5, s85, v2
	v_mad_u64_u32 v[2:3], s[52:53], s84, v2, 0
	v_add3_u32 v3, v3, v4, v5
	v_add_u32_e32 v4, 33, v6
	v_ashrrev_i32_e32 v5, 31, v4
	v_mul_lo_u32 v7, s84, v5
	v_mul_lo_u32 v8, s85, v4
	v_mad_u64_u32 v[4:5], s[52:53], s84, v4, 0
	v_lshl_add_u64 v[2:3], v[2:3], 2, s[28:29]
	v_add3_u32 v5, v5, v7, v8
	v_lshl_add_u64 v[2:3], v[2:3], 0, vcc
	v_lshl_add_u64 v[4:5], v[4:5], 2, s[28:29]
	v_lshl_add_u64 v[2:3], v[2:3], 0, v[0:1]
	v_lshl_add_u64 v[4:5], v[4:5], 0, vcc
	v_lshl_add_u64 v[4:5], v[4:5], 0, v[0:1]
	global_load_dwordx4 v[26:29], v[2:3], off nt
	global_load_dwordx4 v[30:33], v[4:5], off nt
	v_add_u32_e32 v2, 40, v6
	v_ashrrev_i32_e32 v3, 31, v2
	v_mul_lo_u32 v4, s84, v3
	v_mul_lo_u32 v5, s85, v2
	v_mad_u64_u32 v[2:3], s[52:53], s84, v2, 0
	v_add3_u32 v3, v3, v4, v5
	v_add_u32_e32 v4, 41, v6
	v_ashrrev_i32_e32 v5, 31, v4
	v_mul_lo_u32 v7, s84, v5
	v_mul_lo_u32 v8, s85, v4
	v_mad_u64_u32 v[4:5], s[52:53], s84, v4, 0
	v_lshl_add_u64 v[2:3], v[2:3], 2, s[28:29]
	v_add3_u32 v5, v5, v7, v8
	v_lshl_add_u64 v[2:3], v[2:3], 0, vcc
	v_lshl_add_u64 v[4:5], v[4:5], 2, s[28:29]
	v_lshl_add_u64 v[2:3], v[2:3], 0, v[0:1]
	v_lshl_add_u64 v[4:5], v[4:5], 0, vcc
	v_lshl_add_u64 v[4:5], v[4:5], 0, v[0:1]
	global_load_dwordx4 v[18:21], v[2:3], off nt
	global_load_dwordx4 v[22:25], v[4:5], off nt
	v_add_u32_e32 v2, 48, v6
	v_ashrrev_i32_e32 v3, 31, v2
	v_mul_lo_u32 v4, s84, v3
	v_mul_lo_u32 v5, s85, v2
	v_mad_u64_u32 v[2:3], s[52:53], s84, v2, 0
	v_add3_u32 v3, v3, v4, v5
	v_add_u32_e32 v4, 49, v6
	v_ashrrev_i32_e32 v5, 31, v4
	v_mul_lo_u32 v7, s84, v5
	v_mul_lo_u32 v8, s85, v4
	v_mad_u64_u32 v[4:5], s[52:53], s84, v4, 0
	v_lshl_add_u64 v[2:3], v[2:3], 2, s[28:29]
	v_add3_u32 v5, v5, v7, v8
	v_lshl_add_u64 v[2:3], v[2:3], 0, vcc
	v_lshl_add_u64 v[4:5], v[4:5], 2, s[28:29]
	v_lshl_add_u64 v[2:3], v[2:3], 0, v[0:1]
	v_lshl_add_u64 v[4:5], v[4:5], 0, vcc
	v_lshl_add_u64 v[4:5], v[4:5], 0, v[0:1]
	global_load_dwordx4 v[10:13], v[2:3], off nt
	global_load_dwordx4 v[14:17], v[4:5], off nt
	v_add_u32_e32 v2, 56, v6
	v_ashrrev_i32_e32 v3, 31, v2
	v_mul_lo_u32 v4, s84, v3
	v_mul_lo_u32 v5, s85, v2
	v_mad_u64_u32 v[2:3], s[52:53], s84, v2, 0
	v_add3_u32 v3, v3, v4, v5
	v_add_u32_e32 v4, 57, v6
	v_ashrrev_i32_e32 v5, 31, v4
	v_mul_lo_u32 v6, s84, v5
	v_mul_lo_u32 v7, s85, v4
	v_mad_u64_u32 v[4:5], s[52:53], s84, v4, 0
	v_add3_u32 v5, v5, v6, v7
	v_lshl_add_u64 v[2:3], v[2:3], 2, s[28:29]
	v_lshl_add_u64 v[4:5], v[4:5], 2, s[28:29]
	v_lshl_add_u64 v[2:3], v[2:3], 0, vcc
	v_lshl_add_u64 v[4:5], v[4:5], 0, vcc
	v_lshl_add_u64 v[2:3], v[2:3], 0, v[0:1]
	v_lshl_add_u64 v[6:7], v[4:5], 0, v[0:1]
	global_load_dwordx4 v[2:5], v[2:3], off nt
	s_nop 0
	global_load_dwordx4 v[6:9], v[6:7], off nt
	s_waitcnt vmcnt(30) lgkmcnt(0)
	v_cvt_pk_bf16_f32 v130, v122, v126
	v_cvt_pk_bf16_f32 v131, v123, v127
	ds_write2_b32 v191, v130, v131 offset1:32
	v_cvt_pk_bf16_f32 v130, v124, v128
	v_cvt_pk_bf16_f32 v131, v125, v129
	ds_write2_b32 v191, v130, v131 offset0:64 offset1:96
	s_waitcnt vmcnt(28)
	v_cvt_pk_bf16_f32 v130, v114, v118
	v_cvt_pk_bf16_f32 v131, v115, v119
	ds_write2_b32 v192, v130, v131 offset1:32
	v_cvt_pk_bf16_f32 v130, v116, v120
	v_cvt_pk_bf16_f32 v131, v117, v121
	ds_write2_b32 v192, v130, v131 offset0:64 offset1:96
	s_waitcnt vmcnt(26)
	v_cvt_pk_bf16_f32 v130, v106, v110
	v_cvt_pk_bf16_f32 v131, v107, v111
	ds_write2_b32 v193, v130, v131 offset1:32
	v_cvt_pk_bf16_f32 v130, v108, v112
	v_cvt_pk_bf16_f32 v131, v109, v113
	ds_write2_b32 v193, v130, v131 offset0:64 offset1:96
	s_waitcnt vmcnt(24)
	v_cvt_pk_bf16_f32 v130, v98, v102
	v_cvt_pk_bf16_f32 v131, v99, v103
	ds_write2_b32 v194, v130, v131 offset1:32
	v_cvt_pk_bf16_f32 v130, v100, v104
	v_cvt_pk_bf16_f32 v131, v101, v105
	ds_write2_b32 v194, v130, v131 offset0:64 offset1:96
	s_waitcnt vmcnt(22)
	v_cvt_pk_bf16_f32 v130, v74, v78
	v_cvt_pk_bf16_f32 v131, v75, v79
	ds_write2_b32 v195, v130, v131 offset1:32
	v_cvt_pk_bf16_f32 v130, v76, v80
	v_cvt_pk_bf16_f32 v131, v77, v81
	ds_write2_b32 v195, v130, v131 offset0:64 offset1:96
	s_waitcnt vmcnt(20)
	v_cvt_pk_bf16_f32 v130, v66, v70
	v_cvt_pk_bf16_f32 v131, v67, v71
	ds_write2_b32 v196, v130, v131 offset1:32
	v_cvt_pk_bf16_f32 v130, v68, v72
	v_cvt_pk_bf16_f32 v131, v69, v73
	ds_write2_b32 v196, v130, v131 offset0:64 offset1:96
	s_waitcnt vmcnt(18)
	v_cvt_pk_bf16_f32 v130, v42, v46
	v_cvt_pk_bf16_f32 v131, v43, v47
	ds_write2_b32 v197, v130, v131 offset1:32
	v_cvt_pk_bf16_f32 v130, v44, v48
	v_cvt_pk_bf16_f32 v131, v45, v49
	ds_write2_b32 v197, v130, v131 offset0:64 offset1:96
	s_waitcnt vmcnt(16)
	v_cvt_pk_bf16_f32 v130, v34, v38
	v_cvt_pk_bf16_f32 v131, v35, v39
	ds_write2_b32 v198, v130, v131 offset1:32
	v_cvt_pk_bf16_f32 v130, v36, v40
	v_cvt_pk_bf16_f32 v131, v37, v41
	ds_write2_b32 v198, v130, v131 offset0:64 offset1:96
	s_waitcnt lgkmcnt(0)
	ds_read_b128 v[154:157], v176
	ds_read_b128 v[150:153], v178
	ds_read_b128 v[146:149], v180
	ds_read_b128 v[142:145], v182
	ds_read_b128 v[138:141], v184
	ds_read_b128 v[134:137], v186
	ds_read_b128 v[130:133], v188
	s_ashr_i32 s77, s76, 31
	s_and_saveexec_b64 s[28:29], s[22:23]
	s_cbranch_execnz .LBB8_762
	s_or_b64 exec, exec, s[28:29]
	s_and_saveexec_b64 s[28:29], s[4:5]
	s_cbranch_execnz .LBB8_763
